# finalize after residual GEMMs runs on the short-last-round blocks of the following GEMM phase and signals a counter; no grid barrier after it (consumers wait lazily at first use)
# speedup vs baseline: 1.0230x; 1.0133x over previous
.LBB0_7:
	s_cmp_le_i32 s95, s94
	s_cbranch_scc1 .LBB0_700
	s_add_u32 s96, s92, 0x4400000
	s_addc_u32 s97, s93, 0
	s_add_u32 s4, s0, 0x100
	s_addc_u32 s5, s1, 0
	v_writelane_b32 v243, s4, 9
	s_load_dword s98, s[0:1], 0x100
	s_mov_b32 s35, 0
	v_writelane_b32 v243, s5, 10
	v_lshrrev_b32_e32 v1, 20, v0
	v_readlane_b32 s16, v243, 0
	s_cmpk_lt_i32 s16, 0x620
	s_cselect_b64 s[36:37], -1, 0
	s_add_u32 s9, s92, 0x22c80000
	s_addc_u32 s10, s93, 0
	s_add_u32 s4, s92, 0x21680000
	v_writelane_b32 v243, s4, 11
	s_addc_u32 s4, s93, 0
	s_add_u32 s41, s92, 0x1ea80000
	v_writelane_b32 v243, s4, 12
	s_addc_u32 s4, s93, 0
	v_writelane_b32 v243, s4, 13
	s_add_u32 s4, s92, 0x1d480000
	v_writelane_b32 v243, s4, 14
	s_addc_u32 s4, s93, 0
	s_add_u32 s79, s92, 0x1a880000
	v_writelane_b32 v243, s4, 15
	s_addc_u32 s4, s93, 0
	v_writelane_b32 v243, s4, 16
	s_add_u32 s4, s92, 0x25584000
	v_writelane_b32 v243, s4, 17
	s_addc_u32 s4, s93, 0
	v_writelane_b32 v243, s4, 18
	s_add_u32 s4, s92, 0x25771000
	s_addc_u32 s5, s93, 0
	v_writelane_b32 v243, s4, 19
	v_lshrrev_b32_e32 v0, 10, v0
	v_or_b32_e32 v0, v0, v1
	v_writelane_b32 v243, s5, 20
	s_add_u32 s4, s92, 0x25661000
	s_addc_u32 s5, s93, 0
	v_writelane_b32 v243, s4, 21
	s_lshl_b32 s11, s16, 9
	s_waitcnt lgkmcnt(0)
	s_lshl_b32 s99, s98, 3
	v_writelane_b32 v243, s5, 22
	s_lshl_b32 s4, s98, 9
	v_writelane_b32 v243, s4, 23
	s_lshl_b32 s4, s16, 3
	v_writelane_b32 v243, s4, 24
	s_sub_i32 s4, s16, s98
	s_add_i32 s6, s4, 32
	s_max_i32 s4, s6, 0
	s_lshr_b32 s34, s4, 3
	s_lshl_b64 s[4:5], s[34:35], 21
	s_and_b32 s7, s6, 7
	s_cmp_gt_i32 s6, -1
	s_cselect_b32 s6, s7, -1
	v_writelane_b32 v243, s6, 25
	s_add_u32 s6, s92, 0x8800000
	s_addc_u32 s7, s93, 0
	v_writelane_b32 v243, s6, 26
	s_mov_b32 s52, s94
	v_mov_b32_e32 v137, 0
	v_mov_b32_e32 v244, 0
	v_writelane_b32 v243, s7, 27
	s_add_u32 s6, s92, 0x25650000
	v_writelane_b32 v243, s6, 28
	s_addc_u32 s6, s93, 0
	v_writelane_b32 v243, s6, 29
	s_add_u32 s6, s92, 0x25480000
	s_addc_u32 s7, s93, 0
	v_writelane_b32 v243, s6, 30
	v_mov_b32_e32 v162, 0x3727c5ac
	v_mov_b32_e32 v163, 1
	v_writelane_b32 v243, s7, 31
	s_add_u32 s6, s92, 0x18f80000
	s_addc_u32 s7, s93, 0
	v_writelane_b32 v243, s6, 32
	v_mov_b32_e32 v165, 0x41b17218
	s_movk_i32 s76, 0x104
	v_writelane_b32 v243, s7, 33
	s_add_u32 s6, s92, 0x255d9000
	s_addc_u32 s7, s93, 0
	v_writelane_b32 v243, s6, 34
	s_add_u32 s12, s92, 0x1a080000
	s_addc_u32 s13, s93, 0
	v_writelane_b32 v243, s7, 35
	s_lshl_b64 s[6:7], s[34:35], 20
	v_writelane_b32 v243, s12, 36
	s_add_u32 s12, s12, s6
	v_writelane_b32 v243, s13, 37
	s_addc_u32 s13, s13, s7
	v_writelane_b32 v243, s12, 38
	s_add_u32 s4, s9, s4
	s_addc_u32 s5, s10, s5
	v_writelane_b32 v243, s13, 39
	v_writelane_b32 v243, s9, 40
	v_writelane_b32 v243, s10, 41
	v_writelane_b32 v243, s4, 42
	s_movk_i32 s77, 0x3fff
	s_mov_b32 s40, 0x800000
	v_writelane_b32 v243, s5, 43
	s_add_u32 s4, s92, 0x1a480000
	s_addc_u32 s5, s93, 0
	v_writelane_b32 v243, s4, 44
	s_add_u32 s4, s4, s6
	v_writelane_b32 v243, s5, 45
	s_addc_u32 s5, s5, s7
	v_writelane_b32 v243, s4, 46
	s_movk_i32 s42, 0x1600
	s_movk_i32 s43, 0xff7f
	v_writelane_b32 v243, s5, 47
	s_add_u32 s4, s90, s6
	s_addc_u32 s5, s91, s7
	s_add_u32 s6, s4, 0x6688000
	s_addc_u32 s7, s5, 0
	v_writelane_b32 v243, s6, 48
	s_add_u32 s4, s4, 0x6a88000
	s_addc_u32 s5, s5, 0
	v_writelane_b32 v243, s7, 49
	v_writelane_b32 v243, s4, 50
	s_mov_b32 s7, s35
	s_mov_b32 s33, 0xff800000
	v_writelane_b32 v243, s5, 51
	s_add_u32 s4, s92, 0xe580000
	s_addc_u32 s5, s93, 0
	v_writelane_b32 v243, s4, 52
	s_mov_b32 s22, 0x3db504f3
	s_mov_b64 s[26:27], 0x80
	v_writelane_b32 v243, s5, 53
	s_add_u32 s4, s92, 0x15c80000
	s_addc_u32 s5, s93, 0
	s_sub_i32 s6, s16, 64
	s_sub_i32 s12, s98, 64
	v_writelane_b32 v243, s4, 54
	s_cmp_gt_i32 s98, 64
	s_nop 0
	v_writelane_b32 v243, s5, 55
	s_cselect_b64 s[4:5], -1, 0
	s_cmp_gt_i32 s16, 63
	s_cselect_b64 s[14:15], -1, 0
	v_writelane_b32 v243, s14, 56
	s_and_b64 s[4:5], s[14:15], s[4:5]
	s_nop 0
	v_writelane_b32 v243, s15, 57
	v_writelane_b32 v243, s4, 58
	s_nop 1
	v_writelane_b32 v243, s5, 59
	s_add_u32 s4, s92, 0x24e80000
	v_writelane_b32 v243, s4, 60
	s_addc_u32 s4, s93, 0
	v_writelane_b32 v243, s4, 61
	s_add_u32 s4, s92, 0x24880000
	v_writelane_b32 v243, s4, 62
	s_addc_u32 s4, s93, 0
	v_writelane_b32 v243, s4, 63
	s_add_u32 s4, s92, 0x24280000
	v_writelane_b32 v242, s4, 0
	s_addc_u32 s4, s93, 0
	v_writelane_b32 v242, s4, 1
	s_add_u32 s4, s92, 0x23480000
	v_writelane_b32 v242, s4, 2
	s_addc_u32 s4, s93, 0
	v_writelane_b32 v242, s4, 3
	s_mov_b32 s4, s6
	v_writelane_b32 v242, s4, 4
	s_ashr_i32 s13, s12, 31
	s_nop 0
	v_writelane_b32 v242, s5, 5
	s_lshl_b64 s[4:5], s[6:7], 9
	v_writelane_b32 v242, s4, 6
	s_nop 1
	v_writelane_b32 v242, s5, 7
	s_mov_b32 s4, s12
	v_writelane_b32 v242, s4, 8
	s_nop 1
	v_writelane_b32 v242, s5, 9
	s_lshl_b64 s[4:5], s[12:13], 9
	v_writelane_b32 v242, s4, 10
	s_nop 1
	v_writelane_b32 v242, s5, 11
	s_add_u32 s4, s90, 0x4688000
	s_addc_u32 s5, s91, 0
	v_writelane_b32 v242, s4, 12
	s_nop 1
	v_writelane_b32 v242, s5, 13
	s_add_u32 s4, s90, 0x5688000
	s_addc_u32 s5, s91, 0
	v_writelane_b32 v242, s4, 14
	s_nop 1
	v_writelane_b32 v242, s5, 15
	s_mul_hi_i32 s4, s16, 0x55555556
	s_lshr_b32 s5, s4, 31
	s_add_i32 s4, s4, s5
	s_mul_i32 s4, s4, 3
	s_sub_i32 s4, s16, s4
	s_add_i32 s5, s98, -1
	s_cmp_eq_u32 s4, 1
	v_writelane_b32 v242, s5, 16
	s_cselect_b32 s5, 1, 3
	s_cmp_lg_u32 s4, 0
	s_cselect_b32 s4, s5, 0
	v_writelane_b32 v242, s4, 17
	s_add_u32 s4, s90, 0x4400000
	v_writelane_b32 v242, s4, 18
	s_addc_u32 s4, s91, 0
	v_writelane_b32 v242, s4, 19
	s_add_u32 s4, s90, 0x4408000
	v_writelane_b32 v242, s4, 20
	s_addc_u32 s4, s91, 0
	v_writelane_b32 v242, s4, 21
	s_add_u32 s4, s92, 0x25580200
	s_addc_u32 s5, s93, 0
	v_writelane_b32 v242, s4, 22
	s_nop 1
	v_writelane_b32 v242, s5, 23
	s_add_u32 s4, s92, 0x25580400
	s_addc_u32 s5, s93, 0
	v_writelane_b32 v242, s4, 24
	s_nop 1
	v_writelane_b32 v242, s5, 25
	s_add_u32 s4, s92, 0x25580500
	s_addc_u32 s5, s93, 0
	v_writelane_b32 v242, s4, 26
	s_nop 1
	v_writelane_b32 v242, s5, 27
	s_add_u32 s4, s92, 0x25580600
	s_addc_u32 s5, s93, 0
	v_writelane_b32 v242, s4, 28
	s_nop 1
	v_writelane_b32 v242, s5, 29
	s_add_u32 s4, s92, 0x25580700
	s_addc_u32 s5, s93, 0
	v_writelane_b32 v242, s4, 30
	s_nop 1
	v_writelane_b32 v242, s5, 31
	s_add_u32 s4, s92, 0x25580800
	s_addc_u32 s5, s93, 0
	v_writelane_b32 v242, s4, 32
	s_nop 1
	v_writelane_b32 v242, s5, 33
	s_add_u32 s4, s92, 0x25580900
	s_addc_u32 s5, s93, 0
	v_writelane_b32 v242, s4, 34
	s_nop 1
	v_writelane_b32 v242, s5, 35
	s_add_u32 s4, s92, 0x25580a00
	s_addc_u32 s5, s93, 0
	v_writelane_b32 v242, s4, 36
	s_nop 1
	v_writelane_b32 v242, s5, 37
	s_add_u32 s4, s92, 0x25580b00
	s_addc_u32 s5, s93, 0
	v_writelane_b32 v242, s4, 38
	s_nop 1
	v_writelane_b32 v242, s5, 39
	s_add_u32 s4, s92, 0x25580c00
	s_addc_u32 s5, s93, 0
	v_writelane_b32 v242, s4, 40
	s_nop 1
	v_writelane_b32 v242, s5, 41
	s_add_u32 s4, s92, 0x25580d00
	s_addc_u32 s5, s93, 0
	v_writelane_b32 v242, s4, 42
	s_nop 1
	v_writelane_b32 v242, s5, 43
	s_add_u32 s4, s92, 0x25580e00
	s_addc_u32 s5, s93, 0
	v_writelane_b32 v242, s4, 44
	s_nop 1
	v_writelane_b32 v242, s5, 45
	s_add_u32 s4, s92, 0x25580f00
	s_addc_u32 s5, s93, 0
	v_writelane_b32 v242, s4, 46
	s_nop 1
	v_writelane_b32 v242, s5, 47
	s_add_u32 s4, s92, 0x25581000
	s_addc_u32 s5, s93, 0
	v_writelane_b32 v242, s4, 48
	s_nop 1
	v_writelane_b32 v242, s5, 49
	s_add_u32 s4, s92, 0x25581100
	s_addc_u32 s5, s93, 0
	v_writelane_b32 v242, s4, 50
	s_nop 1
	v_writelane_b32 v242, s5, 51
	s_add_u32 s4, s92, 0x25581200
	s_addc_u32 s5, s93, 0
	v_writelane_b32 v242, s4, 52
	s_nop 1
	v_writelane_b32 v242, s5, 53
	s_add_u32 s4, s92, 0x25581300
	s_addc_u32 s5, s93, 0
	v_writelane_b32 v242, s4, 54
	s_cmp_eq_u32 s8, 15
	s_nop 0
	v_writelane_b32 v242, s5, 55
	s_cselect_b64 s[4:5], -1, 0
	v_writelane_b32 v242, s4, 56
	s_cmp_eq_u32 s8, 14
	s_nop 0
	v_writelane_b32 v242, s5, 57
	s_cselect_b64 s[4:5], -1, 0
	v_writelane_b32 v242, s4, 58
	s_cmp_eq_u32 s8, 13
	s_nop 0
	v_writelane_b32 v242, s5, 59
	s_cselect_b64 s[4:5], -1, 0
	v_writelane_b32 v242, s4, 60
	s_cmp_eq_u32 s8, 12
	s_nop 0
	v_writelane_b32 v242, s5, 61
	s_cselect_b64 s[4:5], -1, 0
	v_writelane_b32 v242, s4, 62
	s_cmp_eq_u32 s8, 11
	s_nop 0
	v_writelane_b32 v242, s5, 63
	s_cselect_b64 s[4:5], -1, 0
	v_writelane_b32 v241, s4, 0
	s_cmp_eq_u32 s8, 10
	s_nop 0
	v_writelane_b32 v241, s5, 1
	s_cselect_b64 s[4:5], -1, 0
	v_writelane_b32 v241, s4, 2
	s_cmp_eq_u32 s8, 9
	s_nop 0
	v_writelane_b32 v241, s5, 3
	s_cselect_b64 s[4:5], -1, 0
	v_writelane_b32 v241, s4, 4
	s_cmp_eq_u32 s8, 8
	s_nop 0
	v_writelane_b32 v241, s5, 5
	s_cselect_b64 s[4:5], -1, 0
	v_writelane_b32 v241, s4, 6
	s_cmp_eq_u32 s8, 7
	s_nop 0
	v_writelane_b32 v241, s5, 7
	s_cselect_b64 s[4:5], -1, 0
	v_writelane_b32 v241, s4, 8
	s_cmp_eq_u32 s8, 6
	s_nop 0
	v_writelane_b32 v241, s5, 9
	s_cselect_b64 s[4:5], -1, 0
	v_writelane_b32 v241, s4, 10
	s_cmp_eq_u32 s8, 5
	s_nop 0
	v_writelane_b32 v241, s5, 11
	s_cselect_b64 s[4:5], -1, 0
	v_writelane_b32 v241, s4, 12
	s_cmp_eq_u32 s8, 4
	s_nop 0
	v_writelane_b32 v241, s5, 13
	s_cselect_b64 s[4:5], -1, 0
	v_writelane_b32 v241, s4, 14
	s_cmp_eq_u32 s8, 3
	s_nop 0
	v_writelane_b32 v241, s5, 15
	s_cselect_b64 s[4:5], -1, 0
	v_writelane_b32 v241, s4, 16
	s_cmp_eq_u32 s8, 2
	s_nop 0
	v_writelane_b32 v241, s5, 17
	s_cselect_b64 s[4:5], -1, 0
	v_writelane_b32 v241, s4, 18
	s_cmp_eq_u32 s8, 1
	s_nop 0
	v_writelane_b32 v241, s5, 19
	s_cselect_b64 s[4:5], -1, 0
	v_writelane_b32 v241, s4, 20
	s_cmp_eq_u32 s8, 0
	s_nop 0
	v_writelane_b32 v241, s5, 21
	s_cselect_b64 s[4:5], -1, 0
	v_writelane_b32 v241, s4, 22
	s_nop 1
	v_writelane_b32 v241, s5, 23
	s_lshl_b32 s4, s8, 8
	s_add_u32 s2, s2, s4
	s_addc_u32 s3, s3, 0
	s_add_u32 s2, s2, 0x1400
	s_addc_u32 s3, s3, 0
	v_writelane_b32 v241, s2, 24
	s_nop 1
	v_writelane_b32 v241, s3, 25
	s_movk_i32 s2, 0x3ff
	v_and_or_b32 v0, v0, s2, v147
	s_add_u32 s2, s92, 0x25583400
	s_addc_u32 s3, s93, 0
	v_writelane_b32 v241, s2, 26
	s_nop 1
	v_writelane_b32 v241, s3, 27
	s_abs_i32 s2, s98
	v_cvt_f32_u32_e32 v1, s2
	v_writelane_b32 v241, s2, 28
	s_sub_i32 s2, 0, s2
	v_rcp_iflag_f32_e32 v1, v1
	s_nop 0
	v_mul_f32_e32 v1, 0x4f7ffffe, v1
	v_cvt_u32_f32_e32 v1, v1
	s_nop 0
	v_readfirstlane_b32 s3, v1
	s_mul_i32 s2, s2, s3
	s_mul_hi_u32 s2, s3, s2
	s_add_i32 s2, s3, s2
	v_writelane_b32 v241, s2, 29
	s_lshl_b32 s2, s98, 11
	s_add_i32 s2, s2, 0xfffe0000
	v_writelane_b32 v241, s2, 30
	s_ashr_i32 s2, s98, 31
	v_writelane_b32 v241, s2, 31
	v_writelane_b32 v241, s11, 32
	s_add_i32 s2, s11, 0xffff8000
	v_writelane_b32 v241, s2, 33
	s_add_i32 s2, 0, 0x20000
	v_writelane_b32 v241, s2, 34
	s_add_i32 s2, 0, 0x20004
	v_writelane_b32 v241, s2, 35
	v_cmp_eq_u32_e64 s[2:3], 0, v147
	s_load_dwordx16 s[4:19], s[0:1], 0x0
	v_mbcnt_lo_u32_b32 v1, -1, 0
	v_writelane_b32 v241, s2, 36
	v_mbcnt_hi_u32_b32 v164, -1, v1
	s_nop 0
	v_writelane_b32 v241, s3, 37
	v_cmp_eq_u32_e64 s[2:3], 0, v0
	s_nop 1
	v_writelane_b32 v241, s2, 38
	s_nop 1
	v_writelane_b32 v241, s3, 39
	s_waitcnt lgkmcnt(0)
	v_writelane_b32 v241, s4, 40
	s_nop 1
	v_writelane_b32 v241, s5, 41
	v_writelane_b32 v241, s6, 42
	v_writelane_b32 v241, s7, 43
	v_writelane_b32 v241, s8, 44
	v_writelane_b32 v241, s9, 45
	v_writelane_b32 v241, s10, 46
	v_writelane_b32 v241, s11, 47
	v_writelane_b32 v241, s12, 48
	v_writelane_b32 v241, s13, 49
	v_writelane_b32 v241, s14, 50
	v_writelane_b32 v241, s15, 51
	v_writelane_b32 v241, s16, 52
	v_writelane_b32 v241, s17, 53
	v_writelane_b32 v241, s18, 54
	v_writelane_b32 v241, s19, 55
	s_load_dwordx16 s[60:75], s[0:1], 0x40
	s_load_dwordx16 s[4:19], s[0:1], 0x80
	s_waitcnt lgkmcnt(0)
	v_writelane_b32 v241, s4, 56
	s_nop 1
	v_writelane_b32 v240, s12, 0
	v_writelane_b32 v240, s13, 1
	v_writelane_b32 v240, s14, 2
	v_writelane_b32 v240, s15, 3
	v_writelane_b32 v240, s16, 4
	v_writelane_b32 v240, s17, 5
	v_writelane_b32 v240, s18, 6
	v_writelane_b32 v240, s19, 7
	v_writelane_b32 v240, s41, 8
	v_writelane_b32 v240, s88, 9
	v_writelane_b32 v241, s5, 57
	v_writelane_b32 v241, s6, 58
	v_writelane_b32 v240, s89, 10
	v_writelane_b32 v240, s90, 11
	v_writelane_b32 v240, s91, 12
	v_writelane_b32 v240, s92, 13
	v_writelane_b32 v240, s93, 14
	v_writelane_b32 v240, s94, 15
	v_writelane_b32 v240, s95, 16
	v_writelane_b32 v240, s96, 17
	v_writelane_b32 v241, s7, 59
	v_writelane_b32 v241, s8, 60
	v_writelane_b32 v240, s97, 18
	v_writelane_b32 v240, s98, 19
	v_writelane_b32 v241, s9, 61
	v_writelane_b32 v240, s36, 20
	v_writelane_b32 v241, s10, 62
	v_writelane_b32 v241, s11, 63
	v_writelane_b32 v240, s37, 21
	v_writelane_b32 v240, s79, 22
	s_branch .LBB0_13

.LBB0_59:
	v_readlane_b32 s1, v240, 23
	s_cmp_eq_u32 s1, 6
	s_cselect_b32 s0, 1, 2
	s_cmp_lg_u32 s1, 2
	s_cselect_b32 s0, s0, 0
	s_add_i32 s0, s0, s14
	s_mul_hi_i32 s1, s0, 0x11000
	s_mul_i32 s0, s0, 0x11000
	v_readlane_b32 s6, v243, 17
	s_add_u32 s6, s6, s0
	v_readlane_b32 s0, v243, 18
	s_addc_u32 s7, s0, s1
	v_mov_b32_e32 v2, v147
	v_readlane_b32 s12, v240, 23
	s_cmp_eq_u32 s12, 9
	s_cselect_b32 s0, 1, 0
	s_cmp_eq_u32 s24, 3
	s_cselect_b32 s1, 1, 0
	s_and_b32 s0, s0, s1
	s_cmp_lg_u32 s0, 0
	s_cbranch_scc1 .Lfz_legacy
	s_mov_b32 s15, s12
	v_readlane_b32 s0, v241, 26
	v_readlane_b32 s1, v241, 27
	s_lshl_b32 s12, s52, 2
	s_add_i32 s12, s12, 0x200
	s_add_u32 s0, s0, s12
	s_addc_u32 s1, s1, 0
	v_writelane_b32 v244, s0, 4
	v_writelane_b32 v244, s1, 5
	s_movk_i32 s0, 0xd8
	s_movk_i32 s12, 0x28
	s_cmp_eq_u32 s15, 2
	s_cbranch_scc0 .Lfz_have
	s_movk_i32 s0, 0x98
	s_movk_i32 s12, 0x68
	s_cmp_lt_u32 s24, 2
	s_cbranch_scc0 .Lfz_have
	s_movk_i32 s0, 0xb8
	s_movk_i32 s12, 0x48
.Lfz_have:
	v_writelane_b32 v244, s12, 2
	v_readlane_b32 s1, v243, 0
	s_sub_i32 s1, s1, s0
	v_writelane_b32 v244, s1, 3
	s_cmp_lt_i32 s1, 0
	s_cbranch_scc1 .LBB0_650
	s_lshl_b32 s0, s1, 9
	s_lshl_b32 s1, s1, 3
	s_add_i32 s1, s1, 0x4000
	s_lshl_b32 s15, s12, 3
	s_lshl_b32 s12, s12, 9
	v_writelane_b32 v244, s1, 6
	v_writelane_b32 v244, s15, 7
	s_branch .Lfz_go
.Lfz_legacy:
	s_mov_b32 s0, 0
	v_writelane_b32 v244, s0, 2
	v_readlane_b32 s0, v243, 24
	v_writelane_b32 v244, s0, 6
	v_writelane_b32 v244, s99, 7
	v_readlane_b32 s0, v241, 32
	s_sub_i32 s0, s0, 0x10000
	v_readlane_b32 s12, v243, 23
.Lfz_go:
	s_nop 1
	v_add_u32_e32 v0, s0, v2
	s_movk_i32 s0, 0x4000
	v_cmp_gt_u32_e32 vcc, s0, v0
	s_and_saveexec_b64 s[0:1], vcc
	v_readlane_b32 s10, v243, 21
	v_readlane_b32 s11, v243, 22
	s_cbranch_execz .LBB0_62
	s_mov_b64 s[8:9], 0

.LBB0_62:
	s_or_b64 exec, exec, s[0:1]
	v_ashrrev_i32_e32 v0, 6, v2
	v_readlane_b32 s0, v244, 6
	s_nop 1
	v_add_u32_e32 v136, s0, v0
	s_movk_i32 s0, 0x4400
	v_cmp_gt_i32_e32 vcc, s0, v136
	s_and_saveexec_b64 s[8:9], vcc
	s_cbranch_execz .LBB0_68
	v_and_b32_e32 v4, 63, v2
	v_readlane_b32 s0, v243, 19
	v_lshlrev_b32_e32 v0, 3, v4
	v_mov_b32_e32 v1, v137
	v_lshlrev_b32_e32 v2, 4, v4
	v_mov_b32_e32 v3, v137
	v_readlane_b32 s1, v243, 20
	v_lshl_add_u64 v[0:1], s[96:97], 0, v[0:1]
	v_cmp_eq_u32_e32 vcc, 0, v4
	v_lshl_add_u64 v[2:3], s[0:1], 0, v[2:3]
	s_mov_b64 s[10:11], 0
	s_branch .LBB0_65
.LBB0_64:
	s_or_b64 exec, exec, s[12:13]
	v_readlane_b32 s34, v244, 7
	s_movk_i32 s0, 0x43ff
	s_nop 0
	v_add_u32_e32 v136, s34, v136
	v_cmp_lt_i32_e64 s[0:1], s0, v136
	s_or_b64 s[10:11], s[0:1], s[10:11]
	s_andn2_b64 exec, exec, s[10:11]
	s_cbranch_execz .LBB0_68

.LBB0_122:
	s_cmp_eq_u32 s19, 0
	s_cbranch_scc1 .LBB0_363
	v_readlane_b32 s12, v244, 2
	s_cmp_eq_u32 s12, 0
	s_cbranch_scc1 .Lfm0_done
	s_cmp_lt_i32 s6, 64
	s_cbranch_scc1 .Lfm0_done
	v_readlane_b32 s14, v244, 4
	v_readlane_b32 s15, v244, 5
	s_nop 4
.Lfm0_poll:
	global_load_dword v0, v137, s[14:15] sc1
	s_waitcnt vmcnt(0)
	v_readfirstlane_b32 s13, v0
	s_cmp_ge_u32 s13, s12
	s_cbranch_scc1 .Lfm0_ok
	s_sleep 2
	s_branch .Lfm0_poll
.Lfm0_ok:
	s_mov_b32 s12, 0
	v_writelane_b32 v244, s12, 2
.Lfm0_done:
	v_writelane_b32 v240, s50, 59
	s_ashr_i32 s9, s7, 8
	v_and_b32_e32 v166, 15, v12
	v_writelane_b32 v240, s51, 60
	s_lshl_b32 s50, s9, 6
	s_cmp_eq_u64 s[16:17], 0
	s_cselect_b64 s[14:15], -1, 0
	s_cmp_eq_u32 s41, 1
	s_cselect_b64 s[12:13], -1, 0
	s_or_b64 s[38:39], s[14:15], s[12:13]
	s_waitcnt vmcnt(0)
	v_mov_b32_e32 v173, 0
	s_and_b64 vcc, exec, s[38:39]
	v_mov_b32_e32 v174, 0
	v_mov_b32_e32 v172, 0
	v_mov_b32_e32 v171, 0
	v_mov_b32_e32 v170, 0
	v_mov_b32_e32 v169, 0
	v_mov_b32_e32 v168, 0
	v_mov_b32_e32 v167, 0
	s_cbranch_vccnz .LBB0_125
	v_readlane_b32 s12, v244, 2
	s_cmp_lg_u32 s12, 0
	s_cbranch_scc1 .LBB0_125
	s_lshl_b32 s12, s6, 8
	s_add_i32 s12, s12, s50
	v_or_b32_e32 v0, s12, v166
	v_ashrrev_i32_e32 v1, 31, v0
	v_lshl_add_u64 v[0:1], v[0:1], 2, s[16:17]
	global_load_dword v167, v[0:1], off
	global_load_dword v168, v[0:1], off offset:64
	global_load_dword v169, v[0:1], off offset:128
	global_load_dword v170, v[0:1], off offset:192
	global_load_dword v171, v[0:1], off offset:512
	global_load_dword v172, v[0:1], off offset:576
	global_load_dword v174, v[0:1], off offset:640
	global_load_dword v173, v[0:1], off offset:704

.LBB0_149:
	v_readlane_b32 s34, v244, 2
	s_cmp_eq_u32 s34, 0
	s_cbranch_scc1 .Lfm2_ok
	s_cmp_lt_i32 s23, 64
	s_cbranch_scc1 .Lfm2_ok
	v_readlane_b32 s82, v244, 4
	v_readlane_b32 s83, v244, 5
	s_nop 4
.Lfm2_poll:
	global_load_dword v0, v137, s[82:83] sc1
	s_waitcnt vmcnt(0)
	v_readfirstlane_b32 vcc_lo, v0
	s_cmp_ge_u32 vcc_lo, s34
	s_cbranch_scc1 .Lfm2_ok
	s_sleep 2
	s_branch .Lfm2_poll

.LBB0_153:
	s_lshl_b32 s6, s6, 8
	s_add_i32 s6, s6, s50
	v_or_b32_e32 v152, s6, v166
	v_readlane_b32 s7, v244, 2
	s_cmp_eq_u32 s7, 0
	s_cbranch_scc1 .Lfm1_done
	v_readlane_b32 s92, v244, 4
	v_readlane_b32 s93, v244, 5
	s_nop 4
.Lfm1_poll:
	global_load_dword v128, v137, s[92:93] sc1
	s_waitcnt vmcnt(0)
	v_readfirstlane_b32 s94, v128
	s_cmp_ge_u32 s94, s7
	s_cbranch_scc1 .Lfm1_ok
	s_sleep 2
	s_branch .Lfm1_poll
.Lfm1_ok:
	s_mov_b32 s7, 0
	v_writelane_b32 v244, s7, 2
	s_andn2_b64 vcc, exec, s[78:79]
	s_cbranch_vccnz .Lfm1_done
	v_mov_b32_e32 v128, v152
	v_ashrrev_i32_e32 v129, 31, v152
	v_lshl_add_u64 v[128:129], v[128:129], 2, s[16:17]
	global_load_dword v167, v[128:129], off sc1
	global_load_dword v168, v[128:129], off offset:64 sc1
	global_load_dword v169, v[128:129], off offset:128 sc1
	global_load_dword v170, v[128:129], off offset:192 sc1
	global_load_dword v171, v[128:129], off offset:512 sc1
	global_load_dword v172, v[128:129], off offset:576 sc1
	global_load_dword v174, v[128:129], off offset:640 sc1
	global_load_dword v173, v[128:129], off offset:704 sc1
.Lfm1_done:
	s_mov_b64 s[96:97], -1
	s_mov_b64 s[92:93], 0
	s_cmp_lt_i32 s41, 1
	s_mov_b64 s[94:95], 0
	s_cbranch_scc0 .LBB0_162
	s_and_b64 vcc, exec, s[96:97]
	s_cbranch_vccnz .LBB0_191

.LBB0_650:
	s_add_i32 s14, s52, 1
	s_cmp_ge_i32 s14, s95
	s_mov_b64 s[0:1], -1
	s_cbranch_scc1 .LBB0_12
	s_cmp_eq_u32 s52, 0
	s_cbranch_scc1 .Lfz_bar
	v_readlane_b32 s0, v240, 23
	s_cmp_eq_u32 s0, 2
	s_cbranch_scc1 .Lfz_sig
	s_cmp_eq_u32 s0, 6
	s_cbranch_scc1 .Lfz_sig
	s_cmp_eq_u32 s0, 9
	s_cbranch_scc0 .Lfz_bar
.Lfz_sig:
	s_waitcnt vmcnt(0) lgkmcnt(0)
	s_barrier
	v_readlane_b32 s0, v244, 3
	s_cmp_lt_i32 s0, 0
	s_cbranch_scc1 .LBB0_11
	v_cmp_eq_u32_e32 vcc, 0, v147
	s_and_saveexec_b64 s[0:1], vcc
	s_cbranch_execz .Lfz_sig_done
	buffer_wbl2 sc1
	s_waitcnt vmcnt(0)
	v_readlane_b32 s2, v244, 4
	v_readlane_b32 s3, v244, 5
	s_nop 4
	global_atomic_add v137, v163, s[2:3]
.Lfz_sig_done:
	s_mov_b64 exec, s[0:1]
	s_branch .LBB0_11
.Lfz_bar:
	s_waitcnt vmcnt(0)
	s_waitcnt vmcnt(0) lgkmcnt(0)
	s_barrier
	s_mov_b64 s[0:1], exec
	v_readlane_b32 s2, v241, 36
	v_readlane_b32 s3, v241, 37
	s_and_b64 s[2:3], s[0:1], s[2:3]
	s_mov_b64 exec, s[2:3]
	s_cbranch_execz .LBB0_684
	v_readlane_b32 s2, v241, 34
	s_waitcnt vmcnt(0) expcnt(0) lgkmcnt(0)
	s_nop 0
	v_mov_b32_e32 v0, s2
	ds_read_b32 v1, v0
	v_readlane_b32 s2, v241, 35
	s_waitcnt lgkmcnt(0)
	v_cmp_ne_u32_e32 vcc, 0, v1
	v_mov_b32_e32 v0, s2
	ds_read_b32 v0, v0
	s_cbranch_vccnz .LBB0_668
	v_readlane_b32 s4, v243, 9
	v_readlane_b32 s5, v243, 10
	s_load_dwordx2 s[2:3], s[4:5], 0x0
	s_nop 0
	s_load_dword s4, s[4:5], 0x8
	s_mov_b32 s9, 1
	s_waitcnt lgkmcnt(0)
	s_mul_i32 s8, s3, s2
	s_mul_i32 s8, s8, s4
	s_branch .LBB0_656
